# MLA attention unit prologue: K/V tile loads issued before the Q loads, LDS tile writes wait only for the tile loads, Q waited for at tile-loop entry; on attention zero-hoist stack
# speedup vs baseline: 1.0049x; 1.0049x over previous
.LBB0_514:
	v_readfirstlane_b32 s67, v183
	s_ashr_i32 s69, s67, 6
	s_lshl_b32 s24, s69, 5
	s_and_b32 s65, s24, 0xe0
	v_or_b32_e32 v0, s65, v203
	s_ashr_i32 s24, s67, 9
	v_mul_u32_u24_e32 v0, 0x1800, v0
	v_lshl_add_u64 v[166:167], s[22:23], 0, v[0:1]
	s_mul_i32 s22, s24, 0xc0
	s_ashr_i32 s23, s22, 31
	v_lshl_add_u64 v[166:167], s[22:23], 1, v[166:167]
	v_lshlrev_b32_e32 v0, 1, v182
	v_lshl_add_u64 v[166:167], v[166:167], 0, v[0:1]
	v_lshl_add_u64 v[2:3], s[16:17], 0, v[184:185]
	global_load_dwordx4 v[2:5], v[2:3], off
	v_lshl_add_u64 v[6:7], s[16:17], 0, v[186:187]
	global_load_dwordx4 v[6:9], v[6:7], off
	v_lshl_add_u64 v[10:11], s[18:19], 0, v[188:189]
	v_lshl_add_u64 v[14:15], s[20:21], 0, v[184:185]
	global_load_dwordx4 v[10:13], v[10:11], off
	v_lshl_add_u64 v[18:19], s[20:21], 0, v[186:187]
	global_load_dwordx4 v[14:17], v[14:15], off
	v_lshl_add_u64 v[22:23], s[16:17], 0, v[190:191]
	global_load_dwordx4 v[18:21], v[18:19], off
	v_lshl_add_u64 v[26:27], s[16:17], 0, v[192:193]
	global_load_dwordx4 v[22:25], v[22:23], off
	v_lshl_add_u64 v[30:31], s[18:19], 0, v[222:223]
	global_load_dwordx4 v[26:29], v[26:27], off
	v_lshl_add_u64 v[34:35], s[20:21], 0, v[190:191]
	global_load_dwordx4 v[30:33], v[30:31], off
	v_lshl_add_u64 v[38:39], s[20:21], 0, v[192:193]
	global_load_dwordx4 v[34:37], v[34:35], off
	v_add_u32_e32 v0, v202, v218
	global_load_dwordx4 v[38:41], v[38:39], off
	global_load_dwordx4 v[98:101], v[166:167], off
	global_load_dwordx4 v[102:105], v[166:167], off offset:32
	global_load_dwordx4 v[106:109], v[166:167], off offset:64
	global_load_dwordx4 v[110:113], v[166:167], off offset:96
	global_load_dwordx4 v[114:117], v[166:167], off offset:128
	global_load_dwordx4 v[118:121], v[166:167], off offset:160
	global_load_dwordx4 v[122:125], v[166:167], off offset:192
	global_load_dwordx4 v[126:129], v[166:167], off offset:224
	global_load_dwordx4 v[130:133], v[166:167], off offset:256
	global_load_dwordx4 v[134:137], v[166:167], off offset:288
	global_load_dwordx4 v[138:141], v[166:167], off offset:320
	global_load_dwordx4 v[142:145], v[166:167], off offset:352
	s_and_b32 s22, s67, 0xffffff00
	s_cmpk_eq_i32 s22, 0x100
	s_cselect_b64 s[24:25], -1, 0
	s_cmpk_lg_i32 s22, 0x100
	s_cselect_b64 s[26:27], -1, 0
	v_mov_b64_e32 v[236:237], 0xff
	s_and_b64 vcc, exec, s[26:27]
	v_mov_b32_e32 v42, v1
	v_mov_b32_e32 v43, v1
	v_mov_b32_e32 v44, v1
	v_mov_b32_e32 v45, v1
	v_mov_b32_e32 v46, v1
	v_mov_b32_e32 v47, v1
	v_mov_b32_e32 v48, v1
	v_mov_b32_e32 v49, v1
	v_mov_b32_e32 v50, v1
	v_mov_b32_e32 v51, v1
	v_mov_b32_e32 v52, v1
	v_mov_b32_e32 v53, v1
	v_mov_b32_e32 v54, v1
	v_mov_b32_e32 v55, v1
	v_mov_b32_e32 v56, v1
	v_mov_b32_e32 v57, v1
	v_mov_b32_e32 v58, v1
	v_mov_b32_e32 v59, v1
	v_mov_b32_e32 v60, v1
	v_mov_b32_e32 v61, v1
	v_mov_b32_e32 v62, v1
	v_mov_b32_e32 v63, v1
	v_mov_b32_e32 v64, v1
	v_mov_b32_e32 v65, v1
	v_mov_b32_e32 v66, v1
	v_mov_b32_e32 v67, v1
	v_mov_b32_e32 v68, v1
	v_mov_b32_e32 v69, v1
	v_mov_b32_e32 v70, v1
	v_mov_b32_e32 v71, v1
	v_mov_b32_e32 v72, v1
	v_mov_b32_e32 v73, v1
	v_mov_b32_e32 v74, v1
	v_mov_b32_e32 v75, v1
	v_mov_b32_e32 v76, v1
	v_mov_b32_e32 v77, v1
	v_mov_b32_e32 v78, v1
	v_mov_b32_e32 v79, v1
	v_mov_b32_e32 v80, v1
	v_mov_b32_e32 v81, v1
	v_mov_b32_e32 v82, v1
	v_mov_b32_e32 v83, v1
	v_mov_b32_e32 v84, v1
	v_mov_b32_e32 v85, v1
	v_mov_b32_e32 v86, v1
	v_mov_b32_e32 v87, v1
	v_mov_b32_e32 v88, v1
	v_mov_b32_e32 v89, v1
	v_mov_b32_e32 v90, v1
	v_mov_b32_e32 v91, v1
	v_mov_b32_e32 v92, v1
	v_mov_b32_e32 v93, v1
	v_mov_b32_e32 v94, v1
	v_mov_b32_e32 v95, v1
	v_mov_b32_e32 v96, v1
	v_mov_b32_e32 v97, v1
	v_mov_b32_e32 v239, v1
	v_mov_b32_e32 v240, v1
	s_waitcnt vmcnt(12)
	ds_write_b128 v0, v[2:5]
	v_add_u32_e32 v0, v198, v220
	ds_write_b128 v0, v[6:9]
	ds_write_b128 v234, v[10:13] offset:256
	v_add_u32_e32 v0, v200, v218
	v_lshl_add_u64 v[2:3], s[16:17], 0, v[210:211]
	ds_write_b128 v0, v[14:17] offset:25600
	v_add_u32_e32 v0, v208, v220
	ds_write_b128 v0, v[18:21] offset:25600
	ds_write_b128 v235, v[22:25] offset:46080
	ds_write_b128 v224, v[26:29] offset:46080
	ds_write_b128 v234, v[30:33] offset:46336
	ds_write_b128 v254, v[34:37]
	ds_write_b128 v238, v[38:41]
	global_load_dwordx4 v[146:149], v[2:3], off
	v_lshl_add_u64 v[2:3], s[16:17], 0, v[212:213]
	global_load_dwordx4 v[150:153], v[2:3], off
	v_lshl_add_u64 v[2:3], s[18:19], 0, v[214:215]
	global_load_dwordx4 v[154:157], v[2:3], off
	v_lshl_add_u64 v[2:3], s[20:21], 0, v[210:211]
	global_load_dwordx4 v[158:161], v[2:3], off
	v_lshl_add_u64 v[2:3], s[20:21], 0, v[212:213]
	global_load_dwordx4 v[162:165], v[2:3], off
	s_waitcnt lgkmcnt(0)
	s_barrier
	s_cbranch_vccnz .LBB0_516
	s_setprio 1
.LBB0_516:
	s_add_i32 s70, s68, s28
	s_lshl_b32 s30, s70, 1
	s_cmp_gt_u32 s69, 3
	s_cselect_b64 s[28:29], -1, 0
	v_cndmask_b32_e64 v0, 0, 1, s[28:29]
	v_or_b32_e32 v217, s30, v0
	v_mov_b32_e32 v0, v1
	v_mov_b32_e32 v2, v1
	v_mov_b32_e32 v3, v1
	v_mov_b32_e32 v4, v1
	v_mov_b32_e32 v5, v1
	v_mov_b32_e32 v6, v1
	v_mov_b32_e32 v7, v1
	v_mov_b32_e32 v8, v1
	v_mov_b32_e32 v9, v1
	v_mov_b32_e32 v10, v1
	v_mov_b32_e32 v11, v1
	v_mov_b32_e32 v12, v1
	v_mov_b32_e32 v13, v1
	v_mov_b32_e32 v14, v1
	v_mov_b32_e32 v15, v1
	v_mov_b32_e32 v16, v1
	v_mov_b32_e32 v17, v1
	v_mov_b32_e32 v18, v1
	v_mov_b32_e32 v19, v1
	v_mov_b32_e32 v20, v1
	v_mov_b32_e32 v21, v1
	v_mov_b32_e32 v22, v1
	v_mov_b32_e32 v23, v1
	v_mov_b32_e32 v24, v1
	v_mov_b32_e32 v25, v1
	v_mov_b32_e32 v26, v1
	v_mov_b32_e32 v27, v1
	v_mov_b32_e32 v28, v1
	v_mov_b32_e32 v29, v1
	v_mov_b32_e32 v30, v1
	v_mov_b32_e32 v31, v1
	v_mov_b32_e32 v32, v1
	v_mov_b32_e32 v33, v1
	v_mov_b32_e32 v34, v1
	v_mov_b32_e32 v35, v1
	v_mov_b32_e32 v36, v1
	v_mov_b32_e32 v37, v1
	v_mov_b32_e32 v38, v1
	v_mov_b32_e32 v39, v1
	v_mov_b32_e32 v40, v1
	v_mov_b32_e32 v41, v1
	s_cmp_lt_u32 s69, 4
	s_cselect_b64 s[22:23], -1, 0
	s_mov_b32 s71, 0
	s_cmp_gt_u32 s69, 3
	s_cselect_b32 s100, 1, 0
	s_cselect_b32 s99, -1, 0
	s_mov_b32 s98, 0
	s_waitcnt vmcnt(5)
	s_branch .LBB0_518
